# states phase: chunk-state stores as 16-byte stores (permlane16_swap pairs), 8 per wave instead of 16
# baseline (speedup 1.0000x reference)
; #define LAS __attribute__((address_space(3)))
; __device__ __forceinline__ unsigned cvt_pk_bf16(float lo, float hi) { unsigned r; asm volatile("v_cvt_pk_bf16_f32 %0, %1, %2" : "=v"(r) : "v"(lo), "v"(hi)); return r; }
; __device__ void phase_states(KP P, int layer, LAS unsigned char* lds) {
;     ...
;         for (int ks = 0; ks < 4; ++ks) { const int lb = ks * 32 + q * 8;
;             bf16x8 af[4], bfr[4];
; #pragma unroll
;             for (int pt = 0; pt < 4; ++pt) af[pt] = *(const LAS bf16x8*)(xsw + (pt * 4 + ks) * 1024 + ((lane ^ (2 * pt + (r >> 3))) << 4));
; #pragma unroll
;             for (int nt = 0; nt < 4; ++nt) bfr[nt] = *(const LAS bf16x8*)(BcT + (nt * 16 + r) * 136 + (lb ^ (((2 * nt + (r >> 3)) & 7) << 3)));
; #pragma unroll
;             for (int pt = 0; pt < 4; ++pt)
; #pragma unroll
;                 for (int nt = 0; nt < 4; ++nt) acc[pt][nt] = __builtin_amdgcn_mfma_f32_16x16x32_bf16(bfr[nt], af[pt], acc[pt][nt], 0, 0, 0);
;         }
;         bf16_t* sp = states + (((size_t)bc * 16 + h) << 12);
; #pragma unroll
;         for (int pt = 0; pt < 4; ++pt)
; #pragma unroll
;             for (int nt = 0; nt < 4; ++nt)
;                 { u32x2 o; o.x = cvt_pk_bf16(acc[pt][nt][0], acc[pt][nt][1]); o.y = cvt_pk_bf16(acc[pt][nt][2], acc[pt][nt][3]); *(u32x2*)(sp + (pt * 16 + r) * 64 + nt * 16 + q * 4) = o; }
.LBB0_80:
	v_xor_b32_e32 v71, v64, v227
	v_add_u32_e32 v65, s13, v235
	v_xor_b32_e32 v70, v64, v195
	v_xor_b32_e32 v72, v64, v228
	v_xor_b32_e32 v73, v64, v229
	v_lshl_add_u32 v74, v71, 1, v226
	ds_read_b128 v[66:69], v65
	ds_read_b128 v[74:77], v74 offset:4352
	v_lshl_add_u32 v65, v70, 1, v226
	v_lshl_add_u32 v78, v72, 1, v226
	v_lshl_add_u32 v82, v73, 1, v226
	ds_read_b128 v[70:73], v65
	ds_read_b128 v[78:81], v78 offset:8704
	ds_read_b128 v[82:85], v82 offset:13056
	v_add_u32_e32 v86, s13, v234
	s_waitcnt lgkmcnt(2)
	v_mfma_f32_16x16x32_bf16 v[60:63], v[70:73], v[66:69], v[60:63]
	v_add_u32_e32 v65, s13, v233
	v_add_u32_e32 v64, 32, v64
	v_mfma_f32_16x16x32_bf16 v[56:59], v[74:77], v[66:69], v[56:59]
	s_waitcnt lgkmcnt(1)
	v_mfma_f32_16x16x32_bf16 v[52:55], v[78:81], v[66:69], v[52:55]
	s_waitcnt lgkmcnt(0)
	v_mfma_f32_16x16x32_bf16 v[48:51], v[82:85], v[66:69], v[48:51]
	ds_read_b128 v[66:69], v86
	s_waitcnt lgkmcnt(0)
	v_mfma_f32_16x16x32_bf16 v[44:47], v[70:73], v[66:69], v[44:47]
	v_mfma_f32_16x16x32_bf16 v[40:43], v[74:77], v[66:69], v[40:43]
	v_mfma_f32_16x16x32_bf16 v[36:39], v[78:81], v[66:69], v[36:39]
	v_mfma_f32_16x16x32_bf16 v[32:35], v[82:85], v[66:69], v[32:35]
	ds_read_b128 v[66:69], v65
	v_add_u32_e32 v65, s13, v232
	s_addk_i32 s13, 0x400
	s_waitcnt lgkmcnt(0)
	v_mfma_f32_16x16x32_bf16 v[28:31], v[70:73], v[66:69], v[28:31]
	s_cmpk_eq_i32 s13, 0x1000
	v_mfma_f32_16x16x32_bf16 v[24:27], v[74:77], v[66:69], v[24:27]
	v_mfma_f32_16x16x32_bf16 v[20:23], v[78:81], v[66:69], v[20:23]
	v_mfma_f32_16x16x32_bf16 v[16:19], v[82:85], v[66:69], v[16:19]
	ds_read_b128 v[66:69], v65
	s_waitcnt lgkmcnt(0)
	v_mfma_f32_16x16x32_bf16 v[12:15], v[70:73], v[66:69], v[12:15]
	v_mfma_f32_16x16x32_bf16 v[8:11], v[74:77], v[66:69], v[8:11]
	v_mfma_f32_16x16x32_bf16 v[4:7], v[78:81], v[66:69], v[4:7]
	v_mfma_f32_16x16x32_bf16 v[0:3], v[82:85], v[66:69], v[0:3]
	s_cbranch_scc0 .LBB0_80
	s_ashr_i32 s13, s12, 31
	s_lshl_b64 s[12:13], s[12:13], 17
	s_add_u32 s12, s17, s12
	s_addc_u32 s13, s18, s13
	v_lshlrev_b64 v[64:65], 13, v[180:181]
	v_lshl_add_u64 v[64:65], s[12:13], 0, v[64:65]
	v_mov_b32_e32 v177, v169
	v_lshl_add_u64 v[64:65], v[64:65], 0, v[176:177]
	v_mov_b32_e32 v179, v169
	v_lshl_add_u64 v[64:65], v[64:65], 0, v[178:179]
	v_bfe_u32 v66, v212, 4, 1
	v_mul_u32_u24_e32 v66, 24, v66
	v_mov_b32_e32 v67, 0
	v_lshl_add_u64 v[64:65], v[64:65], 0, v[66:67]
	v_add_co_u32_e32 v66, vcc, s68, v64
	s_nop 1
	v_addc_co_u32_e32 v67, vcc, 0, v65, vcc
	v_cvt_pk_bf16_f32 v60, v60, v61
	v_cvt_pk_bf16_f32 v61, v62, v63
	v_cvt_pk_bf16_f32 v62, v56, v57
	v_cvt_pk_bf16_f32 v63, v58, v59
	s_nop 1
	v_permlane16_swap_b32 v60, v62
	v_permlane16_swap_b32 v61, v63
	global_store_dwordx4 v[64:65], v[60:63], off
	v_cvt_pk_bf16_f32 v52, v52, v53
	v_cvt_pk_bf16_f32 v53, v54, v55
	v_cvt_pk_bf16_f32 v54, v48, v49
	v_cvt_pk_bf16_f32 v55, v50, v51
	s_nop 1
	v_permlane16_swap_b32 v52, v54
	v_permlane16_swap_b32 v53, v55
	global_store_dwordx4 v[64:65], v[52:55], off offset:64
	v_cvt_pk_bf16_f32 v44, v44, v45
	v_cvt_pk_bf16_f32 v45, v46, v47
	v_cvt_pk_bf16_f32 v46, v40, v41
	v_cvt_pk_bf16_f32 v47, v42, v43
	s_nop 1
	v_permlane16_swap_b32 v44, v46
	v_permlane16_swap_b32 v45, v47
	global_store_dwordx4 v[64:65], v[44:47], off offset:2048
	v_cvt_pk_bf16_f32 v36, v36, v37
	v_cvt_pk_bf16_f32 v37, v38, v39
	v_cvt_pk_bf16_f32 v38, v32, v33
	v_cvt_pk_bf16_f32 v39, v34, v35
	s_nop 1
	v_permlane16_swap_b32 v36, v38
	v_permlane16_swap_b32 v37, v39
	global_store_dwordx4 v[64:65], v[36:39], off offset:2112
	v_cvt_pk_bf16_f32 v28, v28, v29
	v_cvt_pk_bf16_f32 v29, v30, v31
	v_cvt_pk_bf16_f32 v30, v24, v25
	v_cvt_pk_bf16_f32 v31, v26, v27
	s_nop 1
	v_permlane16_swap_b32 v28, v30
	v_permlane16_swap_b32 v29, v31
	global_store_dwordx4 v[66:67], v[28:31], off
	v_cvt_pk_bf16_f32 v20, v20, v21
	v_cvt_pk_bf16_f32 v21, v22, v23
	v_cvt_pk_bf16_f32 v22, v16, v17
	v_cvt_pk_bf16_f32 v23, v18, v19
	s_nop 1
	v_permlane16_swap_b32 v20, v22
	v_permlane16_swap_b32 v21, v23
	global_store_dwordx4 v[66:67], v[20:23], off offset:64
	v_cvt_pk_bf16_f32 v12, v12, v13
	v_cvt_pk_bf16_f32 v13, v14, v15
	v_cvt_pk_bf16_f32 v14, v8, v9
	v_cvt_pk_bf16_f32 v15, v10, v11
	s_nop 1
	v_permlane16_swap_b32 v12, v14
	v_permlane16_swap_b32 v13, v15
	global_store_dwordx4 v[66:67], v[12:15], off offset:2048
	v_cvt_pk_bf16_f32 v4, v4, v5
	v_cvt_pk_bf16_f32 v5, v6, v7
	v_cvt_pk_bf16_f32 v6, v0, v1
	v_cvt_pk_bf16_f32 v7, v2, v3
	s_nop 1
	v_permlane16_swap_b32 v4, v6
	v_permlane16_swap_b32 v5, v7
	global_store_dwordx4 v[66:67], v[4:7], off offset:2112
	s_add_i32 s20, s20, s1
	s_cmpk_gt_i32 s20, 0x1ff
	s_barrier
	s_cbranch_scc0 .LBB0_73
